# P0 norm-fold loads de-serialised, with an intermediate vmcnt(24) after the first 32 loads so at most 56 vector-memory ops are ever outstanding per wave
# baseline (speedup 1.0000x reference)
; DI void transpose_w(const float* __restrict__ w, const float* __restrict__ rowscale, bf16_t* __restrict__ out, int K, int N, int bid, int nb, LAS float* tile) {
;     ...
;         for (int q = 0; q < 8; ++q) { const int t = t0 + q * nb; if (t < ntile) { const int k0 = (t % nkt) * 64, n0 = (t / nkt) * 32;
; #pragma unroll
;             for (int it = 0; it < 4; ++it) { const int i = it * 16 + (tid >> 5), j = tid & 31; v[q][it] = w[(size_t)(k0 + i) * N + n0 + j]; if (rowscale) v[q][it] *= rowscale[k0 + i]; } } }
.LBB0_41:
	s_waitcnt vmcnt(24)
	s_add_i32 s87, s78, s83
	s_cmpk_lt_i32 s87, 0x1620
	s_cselect_b64 s[34:35], -1, 0
	s_cmpk_gt_i32 s87, 0x161f
	s_cbranch_scc1 .LBB0_50
	s_ashr_i32 s8, s87, 31
	s_lshr_b32 s8, s8, 27
	s_add_i32 s8, s87, s8
	s_andn2_b32 s8, s8, 31
	s_sub_i32 s9, s87, s8
	v_lshl_or_b32 v16, s9, 6, v3
	s_ashr_i32 s9, s8, 31
	v_lshl_add_u64 v[14:15], s[8:9], 2, v[12:13]
	v_mul_hi_i32_i24_e32 v19, 0x5880, v16
	v_mul_i32_i24_e32 v18, 0x5880, v16
	v_lshl_add_u64 v[18:19], v[14:15], 0, v[18:19]
	global_load_dword v27, v[18:19], off
	v_ashrrev_i32_e32 v17, 31, v16
	s_and_b64 vcc, exec, s[0:1]
	v_lshl_add_u64 v[18:19], v[16:17], 2, s[26:27]
	s_cbranch_vccnz .LBB0_44
	global_load_dword v176, v[18:19], off
